# P3: the first unit's Q'/K' chunk is also requested early, while waiting at the P2->P3 grid barrier
# speedup vs baseline: 1.0002x; 1.0002x over previous
; #define LAS __attribute__((address_space(3)))
;   const bool dry = mode != 0;
;   unsigned char* ws = p.ws;
;   int tid_ = threadIdx.x; asm volatile("" : "+v"(tid_)); const int tid = tid_, wid = __builtin_amdgcn_readfirstlane(tid >> 6), lane = tid & 63, fr = lane & 15, fq = lane >> 4;
;     ...
;   for (int u = blockIdx.x; u < 1024; u += gridDim.x) {
;     const int bh = u >> 6, c = u & 63, h = bh & 3, b = bh >> 2;
;     const float gam = exp2f(lg2gamma(h));
;     {
;       const u32x4* qg = (const u32x4*)(Qr + (long)(bh * 64 + c) * 16384); const u32x4* kg = (const u32x4*)(Kr + (long)(bh * 64 + c) * 16384);
;       u32x4 qv[4], kv[4];
; #pragma unroll
;       for (int i = 0; i < 4; ++i) { qv[i] = qg[tid + i * NTHREADS]; kv[i] = kg[tid + i * NTHREADS]; }
; #pragma unroll
;       for (int i = 0; i < 4; ++i) { *(LAS u32x4*)(shm + RO_Q + (tid + i * NTHREADS) * 16) = qv[i]; *(LAS u32x4*)(shm + RO_K + (tid + i * NTHREADS) * 16) = kv[i]; }
;     }
.LBB0_726:
	s_or_b64 exec, exec, s[6:7]
	s_mov_b32 s100, 0x2000
	s_mov_b32 s101, 0
	s_ashr_i32 s99, s2, 31
	s_mov_b32 s98, s2
	s_lshl_b64 s[98:99], s[98:99], 15
	s_add_u32 s98, s98, s26
	s_addc_u32 s99, s99, s27
	v_lshlrev_b32_e32 v228, 4, v194
	v_mov_b32_e32 v229, 0
	v_lshl_add_u64 v[228:229], s[98:99], 0, v[228:229]
	v_add_co_u32_e32 v230, vcc, 0x4300000, v228
	s_nop 1
	v_addc_co_u32_e32 v231, vcc, 0, v229, vcc
	v_add_co_u32_e32 v228, vcc, 0x2300000, v228
	s_nop 1
	v_addc_co_u32_e32 v229, vcc, 0, v229, vcc
	global_load_dwordx4 v[196:199], v[228:229], off nt
	global_load_dwordx4 v[200:203], v[230:231], off nt
	v_lshl_add_u64 v[228:229], v[228:229], 0, s[100:101]
	v_lshl_add_u64 v[230:231], v[230:231], 0, s[100:101]
	global_load_dwordx4 v[204:207], v[228:229], off nt
	global_load_dwordx4 v[208:211], v[230:231], off nt
	v_lshl_add_u64 v[228:229], v[228:229], 0, s[100:101]
	v_lshl_add_u64 v[230:231], v[230:231], 0, s[100:101]
	global_load_dwordx4 v[212:215], v[228:229], off nt
	global_load_dwordx4 v[216:219], v[230:231], off nt
	v_lshl_add_u64 v[228:229], v[228:229], 0, s[100:101]
	v_lshl_add_u64 v[230:231], v[230:231], 0, s[100:101]
	global_load_dwordx4 v[220:223], v[228:229], off nt
	global_load_dwordx4 v[224:227], v[230:231], off nt
	s_mov_b32 s99, 1
	s_add_u32 s22, s26, 0x2300000
	s_addc_u32 s23, s27, 0
	s_waitcnt vmcnt(27) lgkmcnt(0)
	v_mov_b32_e32 v0, v194
	s_add_u32 s68, s26, 0xc300000
	s_barrier
	s_addc_u32 s69, s27, 0
	s_andn2_b64 vcc, exec, s[0:1]
	v_readfirstlane_b32 s0, v0
	s_cbranch_vccnz .LBB0_755
	s_ashr_i32 s12, s0, 6
	s_lshl_b32 s10, s12, 12
	s_ashr_i32 s11, s10, 31
	s_add_i32 s1, 0, 0x18000
	s_lshl_b64 s[6:7], s[10:11], 1
	s_add_u32 s8, s24, s6
	s_addc_u32 s9, s25, s7
	v_and_b32_e32 v1, 63, v0
	s_waitcnt vmcnt(14)
	v_mov_b32_e32 v91, 0
	s_add_u32 s6, s3, s6
	v_lshlrev_b32_e32 v88, 4, v1
	v_mov_b32_e32 v89, v91
	s_addc_u32 s7, s66, s7
	s_lshl_b32 s3, s12, 4
	s_ashr_i32 s0, s0, 31
	s_waitcnt vmcnt(12)
	v_lshl_add_u64 v[94:95], s[6:7], 0, v[88:89]
	s_or_b32 s6, s3, 15
	s_lshr_b32 s0, s0, 27
	v_and_b32_e32 v3, 15, v0
	s_add_i32 s0, s6, s0
	v_lshl_add_u64 v[92:93], s[8:9], 0, v[88:89]
	s_ashr_i32 s39, s0, 5
	v_or_b32_e32 v89, s3, v3
	s_add_i32 s3, s10, 0
	s_cmpk_gt_i32 s6, 0xffe0
	s_movk_i32 s0, 0x80
	s_cselect_b64 s[40:41], -1, 0
	v_cmp_gt_u32_e64 s[6:7], 16, v1
	v_cmp_gt_i32_e64 s[8:9], s0, v0
	v_lshlrev_b32_e32 v1, 3, v0
	s_add_i32 s11, 0, 0x1a000
	s_mul_i32 s0, s12, 0x2800
	s_waitcnt vmcnt(6)
	v_add_u32_e32 v121, s1, v1
	v_add_u32_e32 v122, s11, v1
	s_add_i32 s13, s0, 0
	v_and_b32_e32 v4, 24, v1
	v_and_b32_e32 v1, 3, v0
	v_lshrrev_b32_e32 v2, 1, v0
	v_lshl_add_u32 v13, v1, 4, s13
	v_lshlrev_b32_e32 v6, 3, v1
	v_ashrrev_i32_e32 v1, 31, v0
	v_lshlrev_b32_e32 v7, 4, v0
	v_and_b32_e32 v9, 24, v2
	v_lshlrev_b32_e32 v2, 8, v0
	v_bfe_u32 v10, v0, 2, 4
	v_lshlrev_b64 v[0:1], 4, v[0:1]
	v_lshlrev_b32_e32 v5, 3, v3
	s_lshl_b32 s30, s12, 10
	v_add_u32_e32 v11, s13, v9
	s_lshl_b32 s0, s12, 5
	v_lshl_add_u64 v[96:97], s[22:23], 0, v[0:1]
	v_lshl_add_u64 v[0:1], s[26:27], 0, v[0:1]
	s_mov_b64 s[12:13], 0x4300000
	v_add_u32_e32 v131, 0, v88
	v_add_u32_e32 v120, s1, v5
	v_add_u32_e32 v123, s11, v5
	v_lshlrev_b32_e32 v8, 10, v10
	v_or_b32_e32 v5, 16, v10
	v_lshl_add_u64 v[98:99], v[0:1], 0, s[12:13]
	v_add_u32_e32 v0, s10, v131
	s_ashr_i32 s1, s0, 31
	v_and_b32_e32 v2, 0x3c00, v2
	v_mul_u32_u24_e32 v15, 0x50, v10
	v_mul_u32_u24_e32 v3, 0x50, v3
	v_mul_u32_u24_e32 v17, 0x50, v5
	v_lshlrev_b32_e32 v10, 10, v5
	v_or_b32_e32 v12, 0x8000, v8
	v_or_b32_e32 v14, 0xc000, v8
	v_or_b32_e32 v16, 0x10000, v8
	v_or_b32_e32 v18, 0x14000, v8
	v_or_b32_e32 v20, 0x18000, v8
	v_or_b32_e32 v22, 0x1c000, v8
	v_add_u32_e32 v132, 0x10000, v0
	v_mbcnt_lo_u32_b32 v0, -1, 0
	s_mov_b32 s18, 0
	s_mov_b32 s19, 0x18000
	s_waitcnt vmcnt(4)
	v_add_u32_e32 v124, 0x80, v123
	v_add_u32_e32 v125, 0x100, v123
	v_add_u32_e32 v126, 0x180, v123
	v_add_u32_e32 v127, 0x200, v123
	v_add_u32_e32 v128, 0x280, v123
	v_add_u32_e32 v129, 0x300, v123
	v_add_u32_e32 v130, 0x380, v123
	s_mov_b32 s31, 0x8000
	s_mov_b32 s38, 0x10000
	s_add_i32 s39, s39, 1
	v_or_b32_e32 v133, 7, v9
	v_add_u32_e32 v134, 0x8000, v131
	v_add_u32_e32 v135, 0, v7
	s_movk_i32 s43, 0x1000
	v_mbcnt_hi_u32_b32 v136, -1, v0
	s_mov_b32 s42, 0x3b800000
	v_add_u32_e32 v137, v11, v3
	s_lshl_b64 s[44:45], s[0:1], 1
	v_lshlrev_b32_e32 v90, 1, v4
	v_lshlrev_b32_e32 v100, 1, v2
	s_mov_b32 s48, 0x20000
	s_mov_b32 s49, 0x28000
	s_mov_b32 s50, 0x30000
	s_mov_b32 s51, 0x38000
	v_lshlrev_b32_e32 v102, 1, v6
	v_add_u32_e32 v138, v13, v15
	v_lshlrev_b32_e32 v104, 1, v8
	v_add_u32_e32 v139, v13, v17
	v_lshlrev_b32_e32 v106, 1, v10
	v_lshlrev_b32_e32 v108, 1, v12
	v_lshlrev_b32_e32 v110, 1, v14
	v_lshlrev_b32_e32 v112, 1, v16
	v_lshlrev_b32_e32 v114, 1, v18
	v_lshlrev_b32_e32 v116, 1, v20
	v_lshlrev_b32_e32 v118, 1, v22
	v_mov_b32_e32 v140, 0x3f7f0000
	v_mov_b32_e32 v141, 0x3f7e0000
	s_mov_b32 s46, s2
	s_mov_b32 s100, 0x2000
	s_mov_b32 s101, 0
	s_branch .LBB0_729
